# GEMM K-loop heads aligned to 64 bytes (s_nop fill)
# speedup vs baseline: 1.0111x; 1.0111x over previous
; template <class Epi, class Sched, bool ALIGN_EPI = false, bool SP2 = false>
; __device__ __forceinline__ void gemm_phase(PG8_LAS unsigned char* lds, const Gemm g, const Sched& S, const Epi& E) {
;     ...
;     for (;;) {
;         const bool has_next = S.next(ui + 1, nxt);
;         const char* nA = has_next ? (const char*)g.A + (size_t)nxt.pm * tstep : cA; const char* nB = has_next ? (const char*)g.Bt + (size_t)nxt.pn * tstep : cB;
;         for (int t = 0; t < nt; t += 2) {
;     ...
; #pragma unroll
;         for (int a = 0; a < 2; ++a)
; #pragma unroll
;             for (int b = 0; b < 2; ++b)
; #pragma unroll
;                 for (int m = 0; m < 4; ++m)
; #pragma unroll
;                     for (int n = 0; n < 2; ++n) acc[a][b][m][n] = (f32x4){0.f, 0.f, 0.f, 0.f};
;         cur = nxt; cA = nA; cB = nB; ++ui;
.LBB0_316:
	v_mov_b32_e32 v125, 0
	s_andn2_b64 vcc, exec, s[44:45]
	v_mov_b32_e32 v124, v125
	v_mov_b32_e32 v123, v125
	v_mov_b32_e32 v122, v125
	v_mov_b32_e32 v117, v125
	v_mov_b32_e32 v116, v125
	v_mov_b32_e32 v115, v125
	v_mov_b32_e32 v114, v125
	v_mov_b32_e32 v109, v125
	v_mov_b32_e32 v108, v125
	v_mov_b32_e32 v107, v125
	v_mov_b32_e32 v106, v125
	v_mov_b32_e32 v101, v125
	v_mov_b32_e32 v100, v125
	v_mov_b32_e32 v99, v125
	v_mov_b32_e32 v98, v125
	v_mov_b32_e32 v93, v125
	v_mov_b32_e32 v92, v125
	v_mov_b32_e32 v91, v125
	v_mov_b32_e32 v90, v125
	v_mov_b32_e32 v85, v125
	v_mov_b32_e32 v84, v125
	v_mov_b32_e32 v83, v125
	v_mov_b32_e32 v82, v125
	v_mov_b32_e32 v77, v125
	v_mov_b32_e32 v76, v125
	v_mov_b32_e32 v75, v125
	v_mov_b32_e32 v74, v125
	v_mov_b32_e32 v69, v125
	v_mov_b32_e32 v68, v125
	v_mov_b32_e32 v67, v125
	v_mov_b32_e32 v66, v125
	v_mov_b32_e32 v129, v125
	v_mov_b32_e32 v128, v125
	v_mov_b32_e32 v127, v125
	v_mov_b32_e32 v126, v125
	v_mov_b32_e32 v121, v125
	v_mov_b32_e32 v120, v125
	v_mov_b32_e32 v119, v125
	v_mov_b32_e32 v118, v125
	v_mov_b32_e32 v113, v125
	v_mov_b32_e32 v112, v125
	v_mov_b32_e32 v111, v125
	v_mov_b32_e32 v110, v125
	v_mov_b32_e32 v105, v125
	v_mov_b32_e32 v104, v125
	v_mov_b32_e32 v103, v125
	v_mov_b32_e32 v102, v125
	v_mov_b32_e32 v97, v125
	v_mov_b32_e32 v96, v125
	v_mov_b32_e32 v95, v125
	v_mov_b32_e32 v94, v125
	v_mov_b32_e32 v89, v125
	v_mov_b32_e32 v88, v125
	v_mov_b32_e32 v87, v125
	v_mov_b32_e32 v86, v125
	v_mov_b32_e32 v81, v125
	v_mov_b32_e32 v80, v125
	v_mov_b32_e32 v79, v125
	v_mov_b32_e32 v78, v125
	v_mov_b32_e32 v73, v125
	v_mov_b32_e32 v72, v125
	v_mov_b32_e32 v71, v125
	v_mov_b32_e32 v70, v125
	v_mov_b32_e32 v61, v125
	v_mov_b32_e32 v60, v125
	v_mov_b32_e32 v59, v125
	v_mov_b32_e32 v58, v125
	v_mov_b32_e32 v53, v125
	v_mov_b32_e32 v52, v125
	v_mov_b32_e32 v51, v125
	v_mov_b32_e32 v50, v125
	v_mov_b32_e32 v45, v125
	v_mov_b32_e32 v44, v125
	v_mov_b32_e32 v43, v125
	v_mov_b32_e32 v42, v125
	v_mov_b32_e32 v37, v125
	v_mov_b32_e32 v36, v125
	v_mov_b32_e32 v35, v125
	v_mov_b32_e32 v34, v125
	v_mov_b32_e32 v29, v125
	v_mov_b32_e32 v28, v125
	v_mov_b32_e32 v27, v125
	v_mov_b32_e32 v26, v125
	v_mov_b32_e32 v21, v125
	v_mov_b32_e32 v20, v125
	v_mov_b32_e32 v19, v125
	v_mov_b32_e32 v18, v125
	v_mov_b32_e32 v13, v125
	v_mov_b32_e32 v12, v125
	v_mov_b32_e32 v11, v125
	v_mov_b32_e32 v10, v125
	v_mov_b32_e32 v9, v125
	v_mov_b32_e32 v8, v125
	v_mov_b32_e32 v7, v125
	v_mov_b32_e32 v6, v125
	v_mov_b32_e32 v65, v125
	v_mov_b32_e32 v64, v125
	v_mov_b32_e32 v63, v125
	v_mov_b32_e32 v62, v125
	v_mov_b32_e32 v57, v125
	v_mov_b32_e32 v56, v125
	v_mov_b32_e32 v55, v125
	v_mov_b32_e32 v54, v125
	v_mov_b32_e32 v49, v125
	v_mov_b32_e32 v48, v125
	v_mov_b32_e32 v47, v125
	v_mov_b32_e32 v46, v125
	v_mov_b32_e32 v41, v125
	v_mov_b32_e32 v40, v125
	v_mov_b32_e32 v39, v125
	v_mov_b32_e32 v38, v125
	v_mov_b32_e32 v33, v125
	v_mov_b32_e32 v32, v125
	v_mov_b32_e32 v31, v125
	v_mov_b32_e32 v30, v125
	v_mov_b32_e32 v25, v125
	v_mov_b32_e32 v24, v125
	v_mov_b32_e32 v23, v125
	v_mov_b32_e32 v22, v125
	v_mov_b32_e32 v17, v125
	v_mov_b32_e32 v16, v125
	v_mov_b32_e32 v15, v125
	v_mov_b32_e32 v14, v125
	v_mov_b32_e32 v5, v125
	v_mov_b32_e32 v4, v125
	v_mov_b32_e32 v3, v125
	v_mov_b32_e32 v2, v125
	s_cbranch_vccnz .LBB0_320
	s_add_u32 s80, s80, 0x80
	s_addc_u32 s81, s81, 0
	s_add_u32 s57, s90, 0x100
	v_mov_b32_e32 v2, 0
	s_addc_u32 s58, s91, 0
	s_mov_b32 s59, 0
	v_mov_b32_e32 v3, v2
	v_mov_b32_e32 v4, v2
	v_mov_b32_e32 v5, v2
	v_mov_b32_e32 v14, v2
	v_mov_b32_e32 v15, v2
	v_mov_b32_e32 v16, v2
	v_mov_b32_e32 v17, v2
	v_mov_b32_e32 v22, v2
	v_mov_b32_e32 v23, v2
	v_mov_b32_e32 v24, v2
	v_mov_b32_e32 v25, v2
	v_mov_b32_e32 v30, v2
	v_mov_b32_e32 v31, v2
	v_mov_b32_e32 v32, v2
	v_mov_b32_e32 v33, v2
	v_mov_b32_e32 v38, v2
	v_mov_b32_e32 v39, v2
	v_mov_b32_e32 v40, v2
	v_mov_b32_e32 v41, v2
	v_mov_b32_e32 v46, v2
	v_mov_b32_e32 v47, v2
	v_mov_b32_e32 v48, v2
	v_mov_b32_e32 v49, v2
	v_mov_b32_e32 v54, v2
	v_mov_b32_e32 v55, v2
	v_mov_b32_e32 v56, v2
	v_mov_b32_e32 v57, v2
	v_mov_b32_e32 v62, v2
	v_mov_b32_e32 v63, v2
	v_mov_b32_e32 v64, v2
	v_mov_b32_e32 v65, v2
	v_mov_b32_e32 v6, v2
	v_mov_b32_e32 v7, v2
	v_mov_b32_e32 v8, v2
	v_mov_b32_e32 v9, v2
	v_mov_b32_e32 v10, v2
	v_mov_b32_e32 v11, v2
	v_mov_b32_e32 v12, v2
	v_mov_b32_e32 v13, v2
	v_mov_b32_e32 v18, v2
	v_mov_b32_e32 v19, v2
	v_mov_b32_e32 v20, v2
	v_mov_b32_e32 v21, v2
	v_mov_b32_e32 v26, v2
	v_mov_b32_e32 v27, v2
	v_mov_b32_e32 v28, v2
	v_mov_b32_e32 v29, v2
	v_mov_b32_e32 v34, v2
	v_mov_b32_e32 v35, v2
	v_mov_b32_e32 v36, v2
	v_mov_b32_e32 v37, v2
	v_mov_b32_e32 v42, v2
	v_mov_b32_e32 v43, v2
	v_mov_b32_e32 v44, v2
	v_mov_b32_e32 v45, v2
	v_mov_b32_e32 v50, v2
	v_mov_b32_e32 v51, v2
	v_mov_b32_e32 v52, v2
	v_mov_b32_e32 v53, v2
	v_mov_b32_e32 v58, v2
	v_mov_b32_e32 v59, v2
	v_mov_b32_e32 v60, v2
	v_mov_b32_e32 v61, v2
	v_mov_b32_e32 v70, v2
	v_mov_b32_e32 v71, v2
	v_mov_b32_e32 v72, v2
	v_mov_b32_e32 v73, v2
	v_mov_b32_e32 v78, v2
	v_mov_b32_e32 v79, v2
	v_mov_b32_e32 v80, v2
	v_mov_b32_e32 v81, v2
	v_mov_b32_e32 v86, v2
	v_mov_b32_e32 v87, v2
	v_mov_b32_e32 v88, v2
	v_mov_b32_e32 v89, v2
	v_mov_b32_e32 v94, v2
	v_mov_b32_e32 v95, v2
	v_mov_b32_e32 v96, v2
	v_mov_b32_e32 v97, v2
	v_mov_b32_e32 v102, v2
	v_mov_b32_e32 v103, v2
	v_mov_b32_e32 v104, v2
	v_mov_b32_e32 v105, v2
	v_mov_b32_e32 v110, v2
	v_mov_b32_e32 v111, v2
	v_mov_b32_e32 v112, v2
	v_mov_b32_e32 v113, v2
	v_mov_b32_e32 v118, v2
	v_mov_b32_e32 v119, v2
	v_mov_b32_e32 v120, v2
	v_mov_b32_e32 v121, v2
	v_mov_b32_e32 v126, v2
	v_mov_b32_e32 v127, v2
	v_mov_b32_e32 v128, v2
	v_mov_b32_e32 v129, v2
	v_mov_b32_e32 v66, v2
	v_mov_b32_e32 v67, v2
	v_mov_b32_e32 v68, v2
	v_mov_b32_e32 v69, v2
	v_mov_b32_e32 v74, v2
	v_mov_b32_e32 v75, v2
	v_mov_b32_e32 v76, v2
	v_mov_b32_e32 v77, v2
	v_mov_b32_e32 v82, v2
	v_mov_b32_e32 v83, v2
	v_mov_b32_e32 v84, v2
	v_mov_b32_e32 v85, v2
	v_mov_b32_e32 v90, v2
	v_mov_b32_e32 v91, v2
	v_mov_b32_e32 v92, v2
	v_mov_b32_e32 v93, v2
	v_mov_b32_e32 v98, v2
	v_mov_b32_e32 v99, v2
	v_mov_b32_e32 v100, v2
	v_mov_b32_e32 v101, v2
	v_mov_b32_e32 v106, v2
	v_mov_b32_e32 v107, v2
	v_mov_b32_e32 v108, v2
	v_mov_b32_e32 v109, v2
	v_mov_b32_e32 v114, v2
	v_mov_b32_e32 v115, v2
	v_mov_b32_e32 v116, v2
	v_mov_b32_e32 v117, v2
	v_mov_b32_e32 v122, v2
	v_mov_b32_e32 v123, v2
	v_mov_b32_e32 v124, v2
	v_mov_b32_e32 v125, v2
	.p2alignl 6, 3212836864

; template <class Epi, class Sched, bool ALIGN_EPI = false, bool SP2 = false>
; __device__ __forceinline__ void gemm_phase(PG8_LAS unsigned char* lds, const Gemm g, const Sched& S, const Epi& E) {
;     ...
;     for (;;) {
;         const bool has_next = S.next(ui + 1, nxt);
;         const char* nA = has_next ? (const char*)g.A + (size_t)nxt.pm * tstep : cA; const char* nB = has_next ? (const char*)g.Bt + (size_t)nxt.pn * tstep : cB;
;         for (int t = 0; t < nt; t += 2) {
;     ...
; #pragma unroll
;         for (int a = 0; a < 2; ++a)
; #pragma unroll
;             for (int b = 0; b < 2; ++b)
; #pragma unroll
;                 for (int m = 0; m < 4; ++m)
; #pragma unroll
;                     for (int n = 0; n < 2; ++n) acc[a][b][m][n] = (f32x4){0.f, 0.f, 0.f, 0.f};
;         cur = nxt; cA = nA; cB = nB; ++ui;
.LBB0_392:
	v_mov_b32_e32 v129, 0
	s_andn2_b64 vcc, exec, s[68:69]
	v_mov_b32_e32 v128, v129
	v_mov_b32_e32 v127, v129
	v_mov_b32_e32 v126, v129
	v_mov_b32_e32 v125, v129
	v_mov_b32_e32 v124, v129
	v_mov_b32_e32 v123, v129
	v_mov_b32_e32 v122, v129
	v_mov_b32_e32 v113, v129
	v_mov_b32_e32 v112, v129
	v_mov_b32_e32 v111, v129
	v_mov_b32_e32 v110, v129
	v_mov_b32_e32 v109, v129
	v_mov_b32_e32 v108, v129
	v_mov_b32_e32 v107, v129
	v_mov_b32_e32 v106, v129
	v_mov_b32_e32 v97, v129
	v_mov_b32_e32 v96, v129
	v_mov_b32_e32 v95, v129
	v_mov_b32_e32 v94, v129
	v_mov_b32_e32 v93, v129
	v_mov_b32_e32 v92, v129
	v_mov_b32_e32 v91, v129
	v_mov_b32_e32 v90, v129
	v_mov_b32_e32 v81, v129
	v_mov_b32_e32 v80, v129
	v_mov_b32_e32 v79, v129
	v_mov_b32_e32 v78, v129
	v_mov_b32_e32 v77, v129
	v_mov_b32_e32 v76, v129
	v_mov_b32_e32 v75, v129
	v_mov_b32_e32 v74, v129
	v_mov_b32_e32 v121, v129
	v_mov_b32_e32 v120, v129
	v_mov_b32_e32 v119, v129
	v_mov_b32_e32 v118, v129
	v_mov_b32_e32 v117, v129
	v_mov_b32_e32 v116, v129
	v_mov_b32_e32 v115, v129
	v_mov_b32_e32 v114, v129
	v_mov_b32_e32 v105, v129
	v_mov_b32_e32 v104, v129
	v_mov_b32_e32 v103, v129
	v_mov_b32_e32 v102, v129
	v_mov_b32_e32 v101, v129
	v_mov_b32_e32 v100, v129
	v_mov_b32_e32 v99, v129
	v_mov_b32_e32 v98, v129
	v_mov_b32_e32 v89, v129
	v_mov_b32_e32 v88, v129
	v_mov_b32_e32 v87, v129
	v_mov_b32_e32 v86, v129
	v_mov_b32_e32 v85, v129
	v_mov_b32_e32 v84, v129
	v_mov_b32_e32 v83, v129
	v_mov_b32_e32 v82, v129
	v_mov_b32_e32 v73, v129
	v_mov_b32_e32 v72, v129
	v_mov_b32_e32 v71, v129
	v_mov_b32_e32 v70, v129
	v_mov_b32_e32 v69, v129
	v_mov_b32_e32 v68, v129
	v_mov_b32_e32 v67, v129
	v_mov_b32_e32 v66, v129
	v_mov_b32_e32 v65, v129
	v_mov_b32_e32 v64, v129
	v_mov_b32_e32 v63, v129
	v_mov_b32_e32 v62, v129
	v_mov_b32_e32 v61, v129
	v_mov_b32_e32 v60, v129
	v_mov_b32_e32 v59, v129
	v_mov_b32_e32 v58, v129
	v_mov_b32_e32 v49, v129
	v_mov_b32_e32 v48, v129
	v_mov_b32_e32 v47, v129
	v_mov_b32_e32 v46, v129
	v_mov_b32_e32 v45, v129
	v_mov_b32_e32 v44, v129
	v_mov_b32_e32 v43, v129
	v_mov_b32_e32 v42, v129
	v_mov_b32_e32 v33, v129
	v_mov_b32_e32 v32, v129
	v_mov_b32_e32 v31, v129
	v_mov_b32_e32 v30, v129
	v_mov_b32_e32 v29, v129
	v_mov_b32_e32 v28, v129
	v_mov_b32_e32 v27, v129
	v_mov_b32_e32 v26, v129
	v_mov_b32_e32 v17, v129
	v_mov_b32_e32 v16, v129
	v_mov_b32_e32 v15, v129
	v_mov_b32_e32 v14, v129
	v_mov_b32_e32 v13, v129
	v_mov_b32_e32 v12, v129
	v_mov_b32_e32 v11, v129
	v_mov_b32_e32 v10, v129
	v_mov_b32_e32 v57, v129
	v_mov_b32_e32 v56, v129
	v_mov_b32_e32 v55, v129
	v_mov_b32_e32 v54, v129
	v_mov_b32_e32 v53, v129
	v_mov_b32_e32 v52, v129
	v_mov_b32_e32 v51, v129
	v_mov_b32_e32 v50, v129
	v_mov_b32_e32 v41, v129
	v_mov_b32_e32 v40, v129
	v_mov_b32_e32 v39, v129
	v_mov_b32_e32 v38, v129
	v_mov_b32_e32 v37, v129
	v_mov_b32_e32 v36, v129
	v_mov_b32_e32 v35, v129
	v_mov_b32_e32 v34, v129
	v_mov_b32_e32 v25, v129
	v_mov_b32_e32 v24, v129
	v_mov_b32_e32 v23, v129
	v_mov_b32_e32 v22, v129
	v_mov_b32_e32 v21, v129
	v_mov_b32_e32 v20, v129
	v_mov_b32_e32 v19, v129
	v_mov_b32_e32 v18, v129
	v_mov_b32_e32 v9, v129
	v_mov_b32_e32 v8, v129
	v_mov_b32_e32 v7, v129
	v_mov_b32_e32 v6, v129
	v_mov_b32_e32 v5, v129
	v_mov_b32_e32 v4, v129
	v_mov_b32_e32 v3, v129
	v_mov_b32_e32 v2, v129
	s_cbranch_vccnz .LBB0_396
	s_add_u32 s90, s90, 0x80
	s_addc_u32 s91, s91, 0
	s_add_u32 s56, s92, 0x100
	v_mov_b32_e32 v2, 0
	s_addc_u32 s57, s93, 0
	s_mov_b32 s58, 0
	v_mov_b32_e32 v3, v2
	v_mov_b32_e32 v4, v2
	v_mov_b32_e32 v5, v2
	v_mov_b32_e32 v6, v2
	v_mov_b32_e32 v7, v2
	v_mov_b32_e32 v8, v2
	v_mov_b32_e32 v9, v2
	v_mov_b32_e32 v18, v2
	v_mov_b32_e32 v19, v2
	v_mov_b32_e32 v20, v2
	v_mov_b32_e32 v21, v2
	v_mov_b32_e32 v22, v2
	v_mov_b32_e32 v23, v2
	v_mov_b32_e32 v24, v2
	v_mov_b32_e32 v25, v2
	v_mov_b32_e32 v34, v2
	v_mov_b32_e32 v35, v2
	v_mov_b32_e32 v36, v2
	v_mov_b32_e32 v37, v2
	v_mov_b32_e32 v38, v2
	v_mov_b32_e32 v39, v2
	v_mov_b32_e32 v40, v2
	v_mov_b32_e32 v41, v2
	v_mov_b32_e32 v50, v2
	v_mov_b32_e32 v51, v2
	v_mov_b32_e32 v52, v2
	v_mov_b32_e32 v53, v2
	v_mov_b32_e32 v54, v2
	v_mov_b32_e32 v55, v2
	v_mov_b32_e32 v56, v2
	v_mov_b32_e32 v57, v2
	v_mov_b32_e32 v10, v2
	v_mov_b32_e32 v11, v2
	v_mov_b32_e32 v12, v2
	v_mov_b32_e32 v13, v2
	v_mov_b32_e32 v14, v2
	v_mov_b32_e32 v15, v2
	v_mov_b32_e32 v16, v2
	v_mov_b32_e32 v17, v2
	v_mov_b32_e32 v26, v2
	v_mov_b32_e32 v27, v2
	v_mov_b32_e32 v28, v2
	v_mov_b32_e32 v29, v2
	v_mov_b32_e32 v30, v2
	v_mov_b32_e32 v31, v2
	v_mov_b32_e32 v32, v2
	v_mov_b32_e32 v33, v2
	v_mov_b32_e32 v42, v2
	v_mov_b32_e32 v43, v2
	v_mov_b32_e32 v44, v2
	v_mov_b32_e32 v45, v2
	v_mov_b32_e32 v46, v2
	v_mov_b32_e32 v47, v2
	v_mov_b32_e32 v48, v2
	v_mov_b32_e32 v49, v2
	v_mov_b32_e32 v58, v2
	v_mov_b32_e32 v59, v2
	v_mov_b32_e32 v60, v2
	v_mov_b32_e32 v61, v2
	v_mov_b32_e32 v62, v2
	v_mov_b32_e32 v63, v2
	v_mov_b32_e32 v64, v2
	v_mov_b32_e32 v65, v2
	v_mov_b32_e32 v66, v2
	v_mov_b32_e32 v67, v2
	v_mov_b32_e32 v68, v2
	v_mov_b32_e32 v69, v2
	v_mov_b32_e32 v70, v2
	v_mov_b32_e32 v71, v2
	v_mov_b32_e32 v72, v2
	v_mov_b32_e32 v73, v2
	v_mov_b32_e32 v82, v2
	v_mov_b32_e32 v83, v2
	v_mov_b32_e32 v84, v2
	v_mov_b32_e32 v85, v2
	v_mov_b32_e32 v86, v2
	v_mov_b32_e32 v87, v2
	v_mov_b32_e32 v88, v2
	v_mov_b32_e32 v89, v2
	v_mov_b32_e32 v98, v2
	v_mov_b32_e32 v99, v2
	v_mov_b32_e32 v100, v2
	v_mov_b32_e32 v101, v2
	v_mov_b32_e32 v102, v2
	v_mov_b32_e32 v103, v2
	v_mov_b32_e32 v104, v2
	v_mov_b32_e32 v105, v2
	v_mov_b32_e32 v114, v2
	v_mov_b32_e32 v115, v2
	v_mov_b32_e32 v116, v2
	v_mov_b32_e32 v117, v2
	v_mov_b32_e32 v118, v2
	v_mov_b32_e32 v119, v2
	v_mov_b32_e32 v120, v2
	v_mov_b32_e32 v121, v2
	v_mov_b32_e32 v74, v2
	v_mov_b32_e32 v75, v2
	v_mov_b32_e32 v76, v2
	v_mov_b32_e32 v77, v2
	v_mov_b32_e32 v78, v2
	v_mov_b32_e32 v79, v2
	v_mov_b32_e32 v80, v2
	v_mov_b32_e32 v81, v2
	v_mov_b32_e32 v90, v2
	v_mov_b32_e32 v91, v2
	v_mov_b32_e32 v92, v2
	v_mov_b32_e32 v93, v2
	v_mov_b32_e32 v94, v2
	v_mov_b32_e32 v95, v2
	v_mov_b32_e32 v96, v2
	v_mov_b32_e32 v97, v2
	v_mov_b32_e32 v106, v2
	v_mov_b32_e32 v107, v2
	v_mov_b32_e32 v108, v2
	v_mov_b32_e32 v109, v2
	v_mov_b32_e32 v110, v2
	v_mov_b32_e32 v111, v2
	v_mov_b32_e32 v112, v2
	v_mov_b32_e32 v113, v2
	v_mov_b32_e32 v122, v2
	v_mov_b32_e32 v123, v2
	v_mov_b32_e32 v124, v2
	v_mov_b32_e32 v125, v2
	v_mov_b32_e32 v126, v2
	v_mov_b32_e32 v127, v2
	v_mov_b32_e32 v128, v2
	v_mov_b32_e32 v129, v2
	.p2alignl 6, 3212836864

; template <class Epi, class Sched, bool ALIGN_EPI = false, bool SP2 = false>
; __device__ __forceinline__ void gemm_phase(PG8_LAS unsigned char* lds, const Gemm g, const Sched& S, const Epi& E) {
;     ...
;     for (;;) {
;         const bool has_next = S.next(ui + 1, nxt);
;         const char* nA = has_next ? (const char*)g.A + (size_t)nxt.pm * tstep : cA; const char* nB = has_next ? (const char*)g.Bt + (size_t)nxt.pn * tstep : cB;
;         for (int t = 0; t < nt; t += 2) {
;     ...
; #pragma unroll
;         for (int a = 0; a < 2; ++a)
; #pragma unroll
;             for (int b = 0; b < 2; ++b)
; #pragma unroll
;                 for (int m = 0; m < 4; ++m)
; #pragma unroll
;                     for (int n = 0; n < 2; ++n) acc[a][b][m][n] = (f32x4){0.f, 0.f, 0.f, 0.f};
;         cur = nxt; cA = nA; cB = nB; ++ui;
.LBB0_486:
	v_mov_b32_e32 v129, 0
	s_andn2_b64 vcc, exec, s[20:21]
	v_mov_b32_e32 v128, v129
	v_mov_b32_e32 v127, v129
	v_mov_b32_e32 v126, v129
	v_mov_b32_e32 v125, v129
	v_mov_b32_e32 v124, v129
	v_mov_b32_e32 v123, v129
	v_mov_b32_e32 v122, v129
	v_mov_b32_e32 v113, v129
	v_mov_b32_e32 v112, v129
	v_mov_b32_e32 v111, v129
	v_mov_b32_e32 v110, v129
	v_mov_b32_e32 v109, v129
	v_mov_b32_e32 v108, v129
	v_mov_b32_e32 v107, v129
	v_mov_b32_e32 v106, v129
	v_mov_b32_e32 v97, v129
	v_mov_b32_e32 v96, v129
	v_mov_b32_e32 v95, v129
	v_mov_b32_e32 v94, v129
	v_mov_b32_e32 v93, v129
	v_mov_b32_e32 v92, v129
	v_mov_b32_e32 v91, v129
	v_mov_b32_e32 v90, v129
	v_mov_b32_e32 v81, v129
	v_mov_b32_e32 v80, v129
	v_mov_b32_e32 v79, v129
	v_mov_b32_e32 v78, v129
	v_mov_b32_e32 v77, v129
	v_mov_b32_e32 v76, v129
	v_mov_b32_e32 v75, v129
	v_mov_b32_e32 v74, v129
	v_mov_b32_e32 v121, v129
	v_mov_b32_e32 v120, v129
	v_mov_b32_e32 v119, v129
	v_mov_b32_e32 v118, v129
	v_mov_b32_e32 v117, v129
	v_mov_b32_e32 v116, v129
	v_mov_b32_e32 v115, v129
	v_mov_b32_e32 v114, v129
	v_mov_b32_e32 v105, v129
	v_mov_b32_e32 v104, v129
	v_mov_b32_e32 v103, v129
	v_mov_b32_e32 v102, v129
	v_mov_b32_e32 v101, v129
	v_mov_b32_e32 v100, v129
	v_mov_b32_e32 v99, v129
	v_mov_b32_e32 v98, v129
	v_mov_b32_e32 v89, v129
	v_mov_b32_e32 v88, v129
	v_mov_b32_e32 v87, v129
	v_mov_b32_e32 v86, v129
	v_mov_b32_e32 v85, v129
	v_mov_b32_e32 v84, v129
	v_mov_b32_e32 v83, v129
	v_mov_b32_e32 v82, v129
	v_mov_b32_e32 v73, v129
	v_mov_b32_e32 v72, v129
	v_mov_b32_e32 v71, v129
	v_mov_b32_e32 v70, v129
	v_mov_b32_e32 v69, v129
	v_mov_b32_e32 v68, v129
	v_mov_b32_e32 v67, v129
	v_mov_b32_e32 v66, v129
	v_mov_b32_e32 v65, v129
	v_mov_b32_e32 v64, v129
	v_mov_b32_e32 v63, v129
	v_mov_b32_e32 v62, v129
	v_mov_b32_e32 v61, v129
	v_mov_b32_e32 v60, v129
	v_mov_b32_e32 v59, v129
	v_mov_b32_e32 v58, v129
	v_mov_b32_e32 v49, v129
	v_mov_b32_e32 v48, v129
	v_mov_b32_e32 v47, v129
	v_mov_b32_e32 v46, v129
	v_mov_b32_e32 v45, v129
	v_mov_b32_e32 v44, v129
	v_mov_b32_e32 v43, v129
	v_mov_b32_e32 v42, v129
	v_mov_b32_e32 v33, v129
	v_mov_b32_e32 v32, v129
	v_mov_b32_e32 v31, v129
	v_mov_b32_e32 v30, v129
	v_mov_b32_e32 v29, v129
	v_mov_b32_e32 v28, v129
	v_mov_b32_e32 v27, v129
	v_mov_b32_e32 v26, v129
	v_mov_b32_e32 v17, v129
	v_mov_b32_e32 v16, v129
	v_mov_b32_e32 v15, v129
	v_mov_b32_e32 v14, v129
	v_mov_b32_e32 v13, v129
	v_mov_b32_e32 v12, v129
	v_mov_b32_e32 v11, v129
	v_mov_b32_e32 v10, v129
	v_mov_b32_e32 v57, v129
	v_mov_b32_e32 v56, v129
	v_mov_b32_e32 v55, v129
	v_mov_b32_e32 v54, v129
	v_mov_b32_e32 v53, v129
	v_mov_b32_e32 v52, v129
	v_mov_b32_e32 v51, v129
	v_mov_b32_e32 v50, v129
	v_mov_b32_e32 v41, v129
	v_mov_b32_e32 v40, v129
	v_mov_b32_e32 v39, v129
	v_mov_b32_e32 v38, v129
	v_mov_b32_e32 v37, v129
	v_mov_b32_e32 v36, v129
	v_mov_b32_e32 v35, v129
	v_mov_b32_e32 v34, v129
	v_mov_b32_e32 v25, v129
	v_mov_b32_e32 v24, v129
	v_mov_b32_e32 v23, v129
	v_mov_b32_e32 v22, v129
	v_mov_b32_e32 v21, v129
	v_mov_b32_e32 v20, v129
	v_mov_b32_e32 v19, v129
	v_mov_b32_e32 v18, v129
	v_mov_b32_e32 v9, v129
	v_mov_b32_e32 v8, v129
	v_mov_b32_e32 v7, v129
	v_mov_b32_e32 v6, v129
	v_mov_b32_e32 v5, v129
	v_mov_b32_e32 v4, v129
	v_mov_b32_e32 v3, v129
	v_mov_b32_e32 v2, v129
	s_cbranch_vccnz .LBB0_490
	s_add_u32 s78, s78, 0x80
	s_addc_u32 s79, s79, 0
	s_add_u32 s58, s80, 0x100
	v_mov_b32_e32 v2, 0
	s_addc_u32 s59, s81, 0
	s_mov_b32 s60, 0
	v_mov_b32_e32 v3, v2
	v_mov_b32_e32 v4, v2
	v_mov_b32_e32 v5, v2
	v_mov_b32_e32 v6, v2
	v_mov_b32_e32 v7, v2
	v_mov_b32_e32 v8, v2
	v_mov_b32_e32 v9, v2
	v_mov_b32_e32 v18, v2
	v_mov_b32_e32 v19, v2
	v_mov_b32_e32 v20, v2
	v_mov_b32_e32 v21, v2
	v_mov_b32_e32 v22, v2
	v_mov_b32_e32 v23, v2
	v_mov_b32_e32 v24, v2
	v_mov_b32_e32 v25, v2
	v_mov_b32_e32 v34, v2
	v_mov_b32_e32 v35, v2
	v_mov_b32_e32 v36, v2
	v_mov_b32_e32 v37, v2
	v_mov_b32_e32 v38, v2
	v_mov_b32_e32 v39, v2
	v_mov_b32_e32 v40, v2
	v_mov_b32_e32 v41, v2
	v_mov_b32_e32 v50, v2
	v_mov_b32_e32 v51, v2
	v_mov_b32_e32 v52, v2
	v_mov_b32_e32 v53, v2
	v_mov_b32_e32 v54, v2
	v_mov_b32_e32 v55, v2
	v_mov_b32_e32 v56, v2
	v_mov_b32_e32 v57, v2
	v_mov_b32_e32 v10, v2
	v_mov_b32_e32 v11, v2
	v_mov_b32_e32 v12, v2
	v_mov_b32_e32 v13, v2
	v_mov_b32_e32 v14, v2
	v_mov_b32_e32 v15, v2
	v_mov_b32_e32 v16, v2
	v_mov_b32_e32 v17, v2
	v_mov_b32_e32 v26, v2
	v_mov_b32_e32 v27, v2
	v_mov_b32_e32 v28, v2
	v_mov_b32_e32 v29, v2
	v_mov_b32_e32 v30, v2
	v_mov_b32_e32 v31, v2
	v_mov_b32_e32 v32, v2
	v_mov_b32_e32 v33, v2
	v_mov_b32_e32 v42, v2
	v_mov_b32_e32 v43, v2
	v_mov_b32_e32 v44, v2
	v_mov_b32_e32 v45, v2
	v_mov_b32_e32 v46, v2
	v_mov_b32_e32 v47, v2
	v_mov_b32_e32 v48, v2
	v_mov_b32_e32 v49, v2
	v_mov_b32_e32 v58, v2
	v_mov_b32_e32 v59, v2
	v_mov_b32_e32 v60, v2
	v_mov_b32_e32 v61, v2
	v_mov_b32_e32 v62, v2
	v_mov_b32_e32 v63, v2
	v_mov_b32_e32 v64, v2
	v_mov_b32_e32 v65, v2
	v_mov_b32_e32 v66, v2
	v_mov_b32_e32 v67, v2
	v_mov_b32_e32 v68, v2
	v_mov_b32_e32 v69, v2
	v_mov_b32_e32 v70, v2
	v_mov_b32_e32 v71, v2
	v_mov_b32_e32 v72, v2
	v_mov_b32_e32 v73, v2
	v_mov_b32_e32 v82, v2
	v_mov_b32_e32 v83, v2
	v_mov_b32_e32 v84, v2
	v_mov_b32_e32 v85, v2
	v_mov_b32_e32 v86, v2
	v_mov_b32_e32 v87, v2
	v_mov_b32_e32 v88, v2
	v_mov_b32_e32 v89, v2
	v_mov_b32_e32 v98, v2
	v_mov_b32_e32 v99, v2
	v_mov_b32_e32 v100, v2
	v_mov_b32_e32 v101, v2
	v_mov_b32_e32 v102, v2
	v_mov_b32_e32 v103, v2
	v_mov_b32_e32 v104, v2
	v_mov_b32_e32 v105, v2
	v_mov_b32_e32 v114, v2
	v_mov_b32_e32 v115, v2
	v_mov_b32_e32 v116, v2
	v_mov_b32_e32 v117, v2
	v_mov_b32_e32 v118, v2
	v_mov_b32_e32 v119, v2
	v_mov_b32_e32 v120, v2
	v_mov_b32_e32 v121, v2
	v_mov_b32_e32 v74, v2
	v_mov_b32_e32 v75, v2
	v_mov_b32_e32 v76, v2
	v_mov_b32_e32 v77, v2
	v_mov_b32_e32 v78, v2
	v_mov_b32_e32 v79, v2
	v_mov_b32_e32 v80, v2
	v_mov_b32_e32 v81, v2
	v_mov_b32_e32 v90, v2
	v_mov_b32_e32 v91, v2
	v_mov_b32_e32 v92, v2
	v_mov_b32_e32 v93, v2
	v_mov_b32_e32 v94, v2
	v_mov_b32_e32 v95, v2
	v_mov_b32_e32 v96, v2
	v_mov_b32_e32 v97, v2
	v_mov_b32_e32 v106, v2
	v_mov_b32_e32 v107, v2
	v_mov_b32_e32 v108, v2
	v_mov_b32_e32 v109, v2
	v_mov_b32_e32 v110, v2
	v_mov_b32_e32 v111, v2
	v_mov_b32_e32 v112, v2
	v_mov_b32_e32 v113, v2
	v_mov_b32_e32 v122, v2
	v_mov_b32_e32 v123, v2
	v_mov_b32_e32 v124, v2
	v_mov_b32_e32 v125, v2
	v_mov_b32_e32 v126, v2
	v_mov_b32_e32 v127, v2
	v_mov_b32_e32 v128, v2
	v_mov_b32_e32 v129, v2
	.p2alignl 6, 3212836864

; template <class Epi, class Sched, bool ALIGN_EPI = false, bool SP2 = false>
; __device__ __forceinline__ void gemm_phase(PG8_LAS unsigned char* lds, const Gemm g, const Sched& S, const Epi& E) {
;     ...
;     for (;;) {
;         const bool has_next = S.next(ui + 1, nxt);
;         const char* nA = has_next ? (const char*)g.A + (size_t)nxt.pm * tstep : cA; const char* nB = has_next ? (const char*)g.Bt + (size_t)nxt.pn * tstep : cB;
;         for (int t = 0; t < nt; t += 2) {
;     ...
; #pragma unroll
;         for (int a = 0; a < 2; ++a)
; #pragma unroll
;             for (int b = 0; b < 2; ++b)
; #pragma unroll
;                 for (int m = 0; m < 4; ++m)
; #pragma unroll
;                     for (int n = 0; n < 2; ++n) acc[a][b][m][n] = (f32x4){0.f, 0.f, 0.f, 0.f};
;         cur = nxt; cA = nA; cB = nB; ++ui;
.LBB0_992:
	v_mov_b32_e32 v125, 0
	s_andn2_b64 vcc, exec, s[20:21]
	v_mov_b32_e32 v124, v125
	v_mov_b32_e32 v123, v125
	v_mov_b32_e32 v122, v125
	v_mov_b32_e32 v129, v125
	v_mov_b32_e32 v128, v125
	v_mov_b32_e32 v127, v125
	v_mov_b32_e32 v126, v125
	v_mov_b32_e32 v113, v125
	v_mov_b32_e32 v112, v125
	v_mov_b32_e32 v111, v125
	v_mov_b32_e32 v110, v125
	v_mov_b32_e32 v109, v125
	v_mov_b32_e32 v108, v125
	v_mov_b32_e32 v107, v125
	v_mov_b32_e32 v106, v125
	v_mov_b32_e32 v97, v125
	v_mov_b32_e32 v96, v125
	v_mov_b32_e32 v95, v125
	v_mov_b32_e32 v94, v125
	v_mov_b32_e32 v93, v125
	v_mov_b32_e32 v92, v125
	v_mov_b32_e32 v91, v125
	v_mov_b32_e32 v90, v125
	v_mov_b32_e32 v81, v125
	v_mov_b32_e32 v80, v125
	v_mov_b32_e32 v79, v125
	v_mov_b32_e32 v78, v125
	v_mov_b32_e32 v77, v125
	v_mov_b32_e32 v76, v125
	v_mov_b32_e32 v75, v125
	v_mov_b32_e32 v74, v125
	v_mov_b32_e32 v121, v125
	v_mov_b32_e32 v120, v125
	v_mov_b32_e32 v119, v125
	v_mov_b32_e32 v118, v125
	v_mov_b32_e32 v117, v125
	v_mov_b32_e32 v116, v125
	v_mov_b32_e32 v115, v125
	v_mov_b32_e32 v114, v125
	v_mov_b32_e32 v105, v125
	v_mov_b32_e32 v104, v125
	v_mov_b32_e32 v103, v125
	v_mov_b32_e32 v102, v125
	v_mov_b32_e32 v101, v125
	v_mov_b32_e32 v100, v125
	v_mov_b32_e32 v99, v125
	v_mov_b32_e32 v98, v125
	v_mov_b32_e32 v89, v125
	v_mov_b32_e32 v88, v125
	v_mov_b32_e32 v87, v125
	v_mov_b32_e32 v86, v125
	v_mov_b32_e32 v85, v125
	v_mov_b32_e32 v84, v125
	v_mov_b32_e32 v83, v125
	v_mov_b32_e32 v82, v125
	v_mov_b32_e32 v73, v125
	v_mov_b32_e32 v72, v125
	v_mov_b32_e32 v71, v125
	v_mov_b32_e32 v70, v125
	v_mov_b32_e32 v69, v125
	v_mov_b32_e32 v68, v125
	v_mov_b32_e32 v67, v125
	v_mov_b32_e32 v66, v125
	v_mov_b32_e32 v65, v125
	v_mov_b32_e32 v64, v125
	v_mov_b32_e32 v63, v125
	v_mov_b32_e32 v62, v125
	v_mov_b32_e32 v61, v125
	v_mov_b32_e32 v60, v125
	v_mov_b32_e32 v59, v125
	v_mov_b32_e32 v58, v125
	v_mov_b32_e32 v49, v125
	v_mov_b32_e32 v48, v125
	v_mov_b32_e32 v47, v125
	v_mov_b32_e32 v46, v125
	v_mov_b32_e32 v45, v125
	v_mov_b32_e32 v44, v125
	v_mov_b32_e32 v43, v125
	v_mov_b32_e32 v42, v125
	v_mov_b32_e32 v33, v125
	v_mov_b32_e32 v32, v125
	v_mov_b32_e32 v31, v125
	v_mov_b32_e32 v30, v125
	v_mov_b32_e32 v29, v125
	v_mov_b32_e32 v28, v125
	v_mov_b32_e32 v27, v125
	v_mov_b32_e32 v26, v125
	v_mov_b32_e32 v17, v125
	v_mov_b32_e32 v16, v125
	v_mov_b32_e32 v15, v125
	v_mov_b32_e32 v14, v125
	v_mov_b32_e32 v13, v125
	v_mov_b32_e32 v12, v125
	v_mov_b32_e32 v11, v125
	v_mov_b32_e32 v10, v125
	v_mov_b32_e32 v57, v125
	v_mov_b32_e32 v56, v125
	v_mov_b32_e32 v55, v125
	v_mov_b32_e32 v54, v125
	v_mov_b32_e32 v53, v125
	v_mov_b32_e32 v52, v125
	v_mov_b32_e32 v51, v125
	v_mov_b32_e32 v50, v125
	v_mov_b32_e32 v41, v125
	v_mov_b32_e32 v40, v125
	v_mov_b32_e32 v39, v125
	v_mov_b32_e32 v38, v125
	v_mov_b32_e32 v37, v125
	v_mov_b32_e32 v36, v125
	v_mov_b32_e32 v35, v125
	v_mov_b32_e32 v34, v125
	v_mov_b32_e32 v25, v125
	v_mov_b32_e32 v24, v125
	v_mov_b32_e32 v23, v125
	v_mov_b32_e32 v22, v125
	v_mov_b32_e32 v21, v125
	v_mov_b32_e32 v20, v125
	v_mov_b32_e32 v19, v125
	v_mov_b32_e32 v18, v125
	v_mov_b32_e32 v9, v125
	v_mov_b32_e32 v8, v125
	v_mov_b32_e32 v7, v125
	v_mov_b32_e32 v6, v125
	v_mov_b32_e32 v5, v125
	v_mov_b32_e32 v4, v125
	v_mov_b32_e32 v3, v125
	v_mov_b32_e32 v2, v125
	s_cbranch_vccnz .LBB0_995
	s_add_u32 s68, s68, 0x80
	s_addc_u32 s69, s69, 0
	s_add_u32 s57, s78, 0x100
	v_mov_b32_e32 v2, 0
	s_addc_u32 s58, s79, 0
	s_mov_b32 s59, 0
	v_mov_b32_e32 v3, v2
	v_mov_b32_e32 v4, v2
	v_mov_b32_e32 v5, v2
	v_mov_b32_e32 v6, v2
	v_mov_b32_e32 v7, v2
	v_mov_b32_e32 v8, v2
	v_mov_b32_e32 v9, v2
	v_mov_b32_e32 v18, v2
	v_mov_b32_e32 v19, v2
	v_mov_b32_e32 v20, v2
	v_mov_b32_e32 v21, v2
	v_mov_b32_e32 v22, v2
	v_mov_b32_e32 v23, v2
	v_mov_b32_e32 v24, v2
	v_mov_b32_e32 v25, v2
	v_mov_b32_e32 v34, v2
	v_mov_b32_e32 v35, v2
	v_mov_b32_e32 v36, v2
	v_mov_b32_e32 v37, v2
	v_mov_b32_e32 v38, v2
	v_mov_b32_e32 v39, v2
	v_mov_b32_e32 v40, v2
	v_mov_b32_e32 v41, v2
	v_mov_b32_e32 v50, v2
	v_mov_b32_e32 v51, v2
	v_mov_b32_e32 v52, v2
	v_mov_b32_e32 v53, v2
	v_mov_b32_e32 v54, v2
	v_mov_b32_e32 v55, v2
	v_mov_b32_e32 v56, v2
	v_mov_b32_e32 v57, v2
	v_mov_b32_e32 v10, v2
	v_mov_b32_e32 v11, v2
	v_mov_b32_e32 v12, v2
	v_mov_b32_e32 v13, v2
	v_mov_b32_e32 v14, v2
	v_mov_b32_e32 v15, v2
	v_mov_b32_e32 v16, v2
	v_mov_b32_e32 v17, v2
	v_mov_b32_e32 v26, v2
	v_mov_b32_e32 v27, v2
	v_mov_b32_e32 v28, v2
	v_mov_b32_e32 v29, v2
	v_mov_b32_e32 v30, v2
	v_mov_b32_e32 v31, v2
	v_mov_b32_e32 v32, v2
	v_mov_b32_e32 v33, v2
	v_mov_b32_e32 v42, v2
	v_mov_b32_e32 v43, v2
	v_mov_b32_e32 v44, v2
	v_mov_b32_e32 v45, v2
	v_mov_b32_e32 v46, v2
	v_mov_b32_e32 v47, v2
	v_mov_b32_e32 v48, v2
	v_mov_b32_e32 v49, v2
	v_mov_b32_e32 v58, v2
	v_mov_b32_e32 v59, v2
	v_mov_b32_e32 v60, v2
	v_mov_b32_e32 v61, v2
	v_mov_b32_e32 v62, v2
	v_mov_b32_e32 v63, v2
	v_mov_b32_e32 v64, v2
	v_mov_b32_e32 v65, v2
	v_mov_b32_e32 v66, v2
	v_mov_b32_e32 v67, v2
	v_mov_b32_e32 v68, v2
	v_mov_b32_e32 v69, v2
	v_mov_b32_e32 v70, v2
	v_mov_b32_e32 v71, v2
	v_mov_b32_e32 v72, v2
	v_mov_b32_e32 v73, v2
	v_mov_b32_e32 v82, v2
	v_mov_b32_e32 v83, v2
	v_mov_b32_e32 v84, v2
	v_mov_b32_e32 v85, v2
	v_mov_b32_e32 v86, v2
	v_mov_b32_e32 v87, v2
	v_mov_b32_e32 v88, v2
	v_mov_b32_e32 v89, v2
	v_mov_b32_e32 v98, v2
	v_mov_b32_e32 v99, v2
	v_mov_b32_e32 v100, v2
	v_mov_b32_e32 v101, v2
	v_mov_b32_e32 v102, v2
	v_mov_b32_e32 v103, v2
	v_mov_b32_e32 v104, v2
	v_mov_b32_e32 v105, v2
	v_mov_b32_e32 v114, v2
	v_mov_b32_e32 v115, v2
	v_mov_b32_e32 v116, v2
	v_mov_b32_e32 v117, v2
	v_mov_b32_e32 v118, v2
	v_mov_b32_e32 v119, v2
	v_mov_b32_e32 v120, v2
	v_mov_b32_e32 v121, v2
	v_mov_b32_e32 v74, v2
	v_mov_b32_e32 v75, v2
	v_mov_b32_e32 v76, v2
	v_mov_b32_e32 v77, v2
	v_mov_b32_e32 v78, v2
	v_mov_b32_e32 v79, v2
	v_mov_b32_e32 v80, v2
	v_mov_b32_e32 v81, v2
	v_mov_b32_e32 v90, v2
	v_mov_b32_e32 v91, v2
	v_mov_b32_e32 v92, v2
	v_mov_b32_e32 v93, v2
	v_mov_b32_e32 v94, v2
	v_mov_b32_e32 v95, v2
	v_mov_b32_e32 v96, v2
	v_mov_b32_e32 v97, v2
	v_mov_b32_e32 v106, v2
	v_mov_b32_e32 v107, v2
	v_mov_b32_e32 v108, v2
	v_mov_b32_e32 v109, v2
	v_mov_b32_e32 v110, v2
	v_mov_b32_e32 v111, v2
	v_mov_b32_e32 v112, v2
	v_mov_b32_e32 v113, v2
	v_mov_b32_e32 v126, v2
	v_mov_b32_e32 v127, v2
	v_mov_b32_e32 v128, v2
	v_mov_b32_e32 v129, v2
	v_mov_b32_e32 v122, v2
	v_mov_b32_e32 v123, v2
	v_mov_b32_e32 v124, v2
	v_mov_b32_e32 v125, v2
	.p2alignl 6, 3212836864

; template <class Epi, class Sched, bool ALIGN_EPI = false, bool SP2 = false>
; __device__ __forceinline__ void gemm_phase(PG8_LAS unsigned char* lds, const Gemm g, const Sched& S, const Epi& E) {
;     ...
;     for (;;) {
;         const bool has_next = S.next(ui + 1, nxt);
;         const char* nA = has_next ? (const char*)g.A + (size_t)nxt.pm * tstep : cA; const char* nB = has_next ? (const char*)g.Bt + (size_t)nxt.pn * tstep : cB;
;         for (int t = 0; t < nt; t += 2) {
;     ...
; #pragma unroll
;         for (int a = 0; a < 2; ++a)
; #pragma unroll
;             for (int b = 0; b < 2; ++b)
; #pragma unroll
;                 for (int m = 0; m < 4; ++m)
; #pragma unroll
;                     for (int n = 0; n < 2; ++n) acc[a][b][m][n] = (f32x4){0.f, 0.f, 0.f, 0.f};
;         cur = nxt; cA = nA; cB = nB; ++ui;
.LBB0_1097:
	v_mov_b32_e32 v129, 0
	s_andn2_b64 vcc, exec, s[38:39]
	v_mov_b32_e32 v128, v129
	v_mov_b32_e32 v127, v129
	v_mov_b32_e32 v126, v129
	v_mov_b32_e32 v125, v129
	v_mov_b32_e32 v124, v129
	v_mov_b32_e32 v123, v129
	v_mov_b32_e32 v122, v129
	v_mov_b32_e32 v113, v129
	v_mov_b32_e32 v112, v129
	v_mov_b32_e32 v111, v129
	v_mov_b32_e32 v110, v129
	v_mov_b32_e32 v109, v129
	v_mov_b32_e32 v108, v129
	v_mov_b32_e32 v107, v129
	v_mov_b32_e32 v106, v129
	v_mov_b32_e32 v97, v129
	v_mov_b32_e32 v96, v129
	v_mov_b32_e32 v95, v129
	v_mov_b32_e32 v94, v129
	v_mov_b32_e32 v93, v129
	v_mov_b32_e32 v92, v129
	v_mov_b32_e32 v91, v129
	v_mov_b32_e32 v90, v129
	v_mov_b32_e32 v81, v129
	v_mov_b32_e32 v80, v129
	v_mov_b32_e32 v79, v129
	v_mov_b32_e32 v78, v129
	v_mov_b32_e32 v77, v129
	v_mov_b32_e32 v76, v129
	v_mov_b32_e32 v75, v129
	v_mov_b32_e32 v74, v129
	v_mov_b32_e32 v121, v129
	v_mov_b32_e32 v120, v129
	v_mov_b32_e32 v119, v129
	v_mov_b32_e32 v118, v129
	v_mov_b32_e32 v117, v129
	v_mov_b32_e32 v116, v129
	v_mov_b32_e32 v115, v129
	v_mov_b32_e32 v114, v129
	v_mov_b32_e32 v105, v129
	v_mov_b32_e32 v104, v129
	v_mov_b32_e32 v103, v129
	v_mov_b32_e32 v102, v129
	v_mov_b32_e32 v101, v129
	v_mov_b32_e32 v100, v129
	v_mov_b32_e32 v99, v129
	v_mov_b32_e32 v98, v129
	v_mov_b32_e32 v89, v129
	v_mov_b32_e32 v88, v129
	v_mov_b32_e32 v87, v129
	v_mov_b32_e32 v86, v129
	v_mov_b32_e32 v85, v129
	v_mov_b32_e32 v84, v129
	v_mov_b32_e32 v83, v129
	v_mov_b32_e32 v82, v129
	v_mov_b32_e32 v73, v129
	v_mov_b32_e32 v72, v129
	v_mov_b32_e32 v71, v129
	v_mov_b32_e32 v70, v129
	v_mov_b32_e32 v69, v129
	v_mov_b32_e32 v68, v129
	v_mov_b32_e32 v67, v129
	v_mov_b32_e32 v66, v129
	v_mov_b32_e32 v65, v129
	v_mov_b32_e32 v64, v129
	v_mov_b32_e32 v63, v129
	v_mov_b32_e32 v62, v129
	v_mov_b32_e32 v61, v129
	v_mov_b32_e32 v60, v129
	v_mov_b32_e32 v59, v129
	v_mov_b32_e32 v58, v129
	v_mov_b32_e32 v49, v129
	v_mov_b32_e32 v48, v129
	v_mov_b32_e32 v47, v129
	v_mov_b32_e32 v46, v129
	v_mov_b32_e32 v45, v129
	v_mov_b32_e32 v44, v129
	v_mov_b32_e32 v43, v129
	v_mov_b32_e32 v42, v129
	v_mov_b32_e32 v33, v129
	v_mov_b32_e32 v32, v129
	v_mov_b32_e32 v31, v129
	v_mov_b32_e32 v30, v129
	v_mov_b32_e32 v29, v129
	v_mov_b32_e32 v28, v129
	v_mov_b32_e32 v27, v129
	v_mov_b32_e32 v26, v129
	v_mov_b32_e32 v17, v129
	v_mov_b32_e32 v16, v129
	v_mov_b32_e32 v15, v129
	v_mov_b32_e32 v14, v129
	v_mov_b32_e32 v13, v129
	v_mov_b32_e32 v12, v129
	v_mov_b32_e32 v11, v129
	v_mov_b32_e32 v10, v129
	v_mov_b32_e32 v57, v129
	v_mov_b32_e32 v56, v129
	v_mov_b32_e32 v55, v129
	v_mov_b32_e32 v54, v129
	v_mov_b32_e32 v53, v129
	v_mov_b32_e32 v52, v129
	v_mov_b32_e32 v51, v129
	v_mov_b32_e32 v50, v129
	v_mov_b32_e32 v41, v129
	v_mov_b32_e32 v40, v129
	v_mov_b32_e32 v39, v129
	v_mov_b32_e32 v38, v129
	v_mov_b32_e32 v37, v129
	v_mov_b32_e32 v36, v129
	v_mov_b32_e32 v35, v129
	v_mov_b32_e32 v34, v129
	v_mov_b32_e32 v25, v129
	v_mov_b32_e32 v24, v129
	v_mov_b32_e32 v23, v129
	v_mov_b32_e32 v22, v129
	v_mov_b32_e32 v21, v129
	v_mov_b32_e32 v20, v129
	v_mov_b32_e32 v19, v129
	v_mov_b32_e32 v18, v129
	v_mov_b32_e32 v9, v129
	v_mov_b32_e32 v8, v129
	v_mov_b32_e32 v7, v129
	v_mov_b32_e32 v6, v129
	v_mov_b32_e32 v5, v129
	v_mov_b32_e32 v4, v129
	v_mov_b32_e32 v3, v129
	v_mov_b32_e32 v2, v129
	s_cbranch_vccnz .LBB0_1101
	s_add_u32 s80, s80, 0x80
	s_addc_u32 s81, s81, 0
	s_add_u32 s56, s90, 0x100
	v_mov_b32_e32 v2, 0
	s_addc_u32 s57, s91, 0
	s_mov_b32 s58, 0
	v_mov_b32_e32 v3, v2
	v_mov_b32_e32 v4, v2
	v_mov_b32_e32 v5, v2
	v_mov_b32_e32 v6, v2
	v_mov_b32_e32 v7, v2
	v_mov_b32_e32 v8, v2
	v_mov_b32_e32 v9, v2
	v_mov_b32_e32 v18, v2
	v_mov_b32_e32 v19, v2
	v_mov_b32_e32 v20, v2
	v_mov_b32_e32 v21, v2
	v_mov_b32_e32 v22, v2
	v_mov_b32_e32 v23, v2
	v_mov_b32_e32 v24, v2
	v_mov_b32_e32 v25, v2
	v_mov_b32_e32 v34, v2
	v_mov_b32_e32 v35, v2
	v_mov_b32_e32 v36, v2
	v_mov_b32_e32 v37, v2
	v_mov_b32_e32 v38, v2
	v_mov_b32_e32 v39, v2
	v_mov_b32_e32 v40, v2
	v_mov_b32_e32 v41, v2
	v_mov_b32_e32 v50, v2
	v_mov_b32_e32 v51, v2
	v_mov_b32_e32 v52, v2
	v_mov_b32_e32 v53, v2
	v_mov_b32_e32 v54, v2
	v_mov_b32_e32 v55, v2
	v_mov_b32_e32 v56, v2
	v_mov_b32_e32 v57, v2
	v_mov_b32_e32 v10, v2
	v_mov_b32_e32 v11, v2
	v_mov_b32_e32 v12, v2
	v_mov_b32_e32 v13, v2
	v_mov_b32_e32 v14, v2
	v_mov_b32_e32 v15, v2
	v_mov_b32_e32 v16, v2
	v_mov_b32_e32 v17, v2
	v_mov_b32_e32 v26, v2
	v_mov_b32_e32 v27, v2
	v_mov_b32_e32 v28, v2
	v_mov_b32_e32 v29, v2
	v_mov_b32_e32 v30, v2
	v_mov_b32_e32 v31, v2
	v_mov_b32_e32 v32, v2
	v_mov_b32_e32 v33, v2
	v_mov_b32_e32 v42, v2
	v_mov_b32_e32 v43, v2
	v_mov_b32_e32 v44, v2
	v_mov_b32_e32 v45, v2
	v_mov_b32_e32 v46, v2
	v_mov_b32_e32 v47, v2
	v_mov_b32_e32 v48, v2
	v_mov_b32_e32 v49, v2
	v_mov_b32_e32 v58, v2
	v_mov_b32_e32 v59, v2
	v_mov_b32_e32 v60, v2
	v_mov_b32_e32 v61, v2
	v_mov_b32_e32 v62, v2
	v_mov_b32_e32 v63, v2
	v_mov_b32_e32 v64, v2
	v_mov_b32_e32 v65, v2
	v_mov_b32_e32 v66, v2
	v_mov_b32_e32 v67, v2
	v_mov_b32_e32 v68, v2
	v_mov_b32_e32 v69, v2
	v_mov_b32_e32 v70, v2
	v_mov_b32_e32 v71, v2
	v_mov_b32_e32 v72, v2
	v_mov_b32_e32 v73, v2
	v_mov_b32_e32 v82, v2
	v_mov_b32_e32 v83, v2
	v_mov_b32_e32 v84, v2
	v_mov_b32_e32 v85, v2
	v_mov_b32_e32 v86, v2
	v_mov_b32_e32 v87, v2
	v_mov_b32_e32 v88, v2
	v_mov_b32_e32 v89, v2
	v_mov_b32_e32 v98, v2
	v_mov_b32_e32 v99, v2
	v_mov_b32_e32 v100, v2
	v_mov_b32_e32 v101, v2
	v_mov_b32_e32 v102, v2
	v_mov_b32_e32 v103, v2
	v_mov_b32_e32 v104, v2
	v_mov_b32_e32 v105, v2
	v_mov_b32_e32 v114, v2
	v_mov_b32_e32 v115, v2
	v_mov_b32_e32 v116, v2
	v_mov_b32_e32 v117, v2
	v_mov_b32_e32 v118, v2
	v_mov_b32_e32 v119, v2
	v_mov_b32_e32 v120, v2
	v_mov_b32_e32 v121, v2
	v_mov_b32_e32 v74, v2
	v_mov_b32_e32 v75, v2
	v_mov_b32_e32 v76, v2
	v_mov_b32_e32 v77, v2
	v_mov_b32_e32 v78, v2
	v_mov_b32_e32 v79, v2
	v_mov_b32_e32 v80, v2
	v_mov_b32_e32 v81, v2
	v_mov_b32_e32 v90, v2
	v_mov_b32_e32 v91, v2
	v_mov_b32_e32 v92, v2
	v_mov_b32_e32 v93, v2
	v_mov_b32_e32 v94, v2
	v_mov_b32_e32 v95, v2
	v_mov_b32_e32 v96, v2
	v_mov_b32_e32 v97, v2
	v_mov_b32_e32 v106, v2
	v_mov_b32_e32 v107, v2
	v_mov_b32_e32 v108, v2
	v_mov_b32_e32 v109, v2
	v_mov_b32_e32 v110, v2
	v_mov_b32_e32 v111, v2
	v_mov_b32_e32 v112, v2
	v_mov_b32_e32 v113, v2
	v_mov_b32_e32 v122, v2
	v_mov_b32_e32 v123, v2
	v_mov_b32_e32 v124, v2
	v_mov_b32_e32 v125, v2
	v_mov_b32_e32 v126, v2
	v_mov_b32_e32 v127, v2
	v_mov_b32_e32 v128, v2
	v_mov_b32_e32 v129, v2
	.p2alignl 6, 3212836864

; template <class Epi, class Sched, bool ALIGN_EPI = false, bool SP2 = false>
; __device__ __forceinline__ void gemm_phase(PG8_LAS unsigned char* lds, const Gemm g, const Sched& S, const Epi& E) {
;     ...
;     for (;;) {
;         const bool has_next = S.next(ui + 1, nxt);
;         const char* nA = has_next ? (const char*)g.A + (size_t)nxt.pm * tstep : cA; const char* nB = has_next ? (const char*)g.Bt + (size_t)nxt.pn * tstep : cB;
;         for (int t = 0; t < nt; t += 2) {
;     ...
; #pragma unroll
;         for (int a = 0; a < 2; ++a)
; #pragma unroll
;             for (int b = 0; b < 2; ++b)
; #pragma unroll
;                 for (int m = 0; m < 4; ++m)
; #pragma unroll
;                     for (int n = 0; n < 2; ++n) acc[a][b][m][n] = (f32x4){0.f, 0.f, 0.f, 0.f};
;         cur = nxt; cA = nA; cB = nB; ++ui;
.LBB0_1189:
	v_mov_b32_e32 v125, 0
	s_andn2_b64 vcc, exec, s[20:21]
	v_mov_b32_e32 v124, v125
	v_mov_b32_e32 v123, v125
	v_mov_b32_e32 v122, v125
	v_mov_b32_e32 v117, v125
	v_mov_b32_e32 v116, v125
	v_mov_b32_e32 v115, v125
	v_mov_b32_e32 v114, v125
	v_mov_b32_e32 v109, v125
	v_mov_b32_e32 v108, v125
	v_mov_b32_e32 v107, v125
	v_mov_b32_e32 v106, v125
	v_mov_b32_e32 v101, v125
	v_mov_b32_e32 v100, v125
	v_mov_b32_e32 v99, v125
	v_mov_b32_e32 v98, v125
	v_mov_b32_e32 v93, v125
	v_mov_b32_e32 v92, v125
	v_mov_b32_e32 v91, v125
	v_mov_b32_e32 v90, v125
	v_mov_b32_e32 v85, v125
	v_mov_b32_e32 v84, v125
	v_mov_b32_e32 v83, v125
	v_mov_b32_e32 v82, v125
	v_mov_b32_e32 v77, v125
	v_mov_b32_e32 v76, v125
	v_mov_b32_e32 v75, v125
	v_mov_b32_e32 v74, v125
	v_mov_b32_e32 v69, v125
	v_mov_b32_e32 v68, v125
	v_mov_b32_e32 v67, v125
	v_mov_b32_e32 v66, v125
	v_mov_b32_e32 v129, v125
	v_mov_b32_e32 v128, v125
	v_mov_b32_e32 v127, v125
	v_mov_b32_e32 v126, v125
	v_mov_b32_e32 v121, v125
	v_mov_b32_e32 v120, v125
	v_mov_b32_e32 v119, v125
	v_mov_b32_e32 v118, v125
	v_mov_b32_e32 v113, v125
	v_mov_b32_e32 v112, v125
	v_mov_b32_e32 v111, v125
	v_mov_b32_e32 v110, v125
	v_mov_b32_e32 v105, v125
	v_mov_b32_e32 v104, v125
	v_mov_b32_e32 v103, v125
	v_mov_b32_e32 v102, v125
	v_mov_b32_e32 v97, v125
	v_mov_b32_e32 v96, v125
	v_mov_b32_e32 v95, v125
	v_mov_b32_e32 v94, v125
	v_mov_b32_e32 v89, v125
	v_mov_b32_e32 v88, v125
	v_mov_b32_e32 v87, v125
	v_mov_b32_e32 v86, v125
	v_mov_b32_e32 v81, v125
	v_mov_b32_e32 v80, v125
	v_mov_b32_e32 v79, v125
	v_mov_b32_e32 v78, v125
	v_mov_b32_e32 v73, v125
	v_mov_b32_e32 v72, v125
	v_mov_b32_e32 v71, v125
	v_mov_b32_e32 v70, v125
	v_mov_b32_e32 v61, v125
	v_mov_b32_e32 v60, v125
	v_mov_b32_e32 v59, v125
	v_mov_b32_e32 v58, v125
	v_mov_b32_e32 v53, v125
	v_mov_b32_e32 v52, v125
	v_mov_b32_e32 v51, v125
	v_mov_b32_e32 v50, v125
	v_mov_b32_e32 v45, v125
	v_mov_b32_e32 v44, v125
	v_mov_b32_e32 v43, v125
	v_mov_b32_e32 v42, v125
	v_mov_b32_e32 v37, v125
	v_mov_b32_e32 v36, v125
	v_mov_b32_e32 v35, v125
	v_mov_b32_e32 v34, v125
	v_mov_b32_e32 v29, v125
	v_mov_b32_e32 v28, v125
	v_mov_b32_e32 v27, v125
	v_mov_b32_e32 v26, v125
	v_mov_b32_e32 v21, v125
	v_mov_b32_e32 v20, v125
	v_mov_b32_e32 v19, v125
	v_mov_b32_e32 v18, v125
	v_mov_b32_e32 v13, v125
	v_mov_b32_e32 v12, v125
	v_mov_b32_e32 v11, v125
	v_mov_b32_e32 v10, v125
	v_mov_b32_e32 v9, v125
	v_mov_b32_e32 v8, v125
	v_mov_b32_e32 v7, v125
	v_mov_b32_e32 v6, v125
	v_mov_b32_e32 v65, v125
	v_mov_b32_e32 v64, v125
	v_mov_b32_e32 v63, v125
	v_mov_b32_e32 v62, v125
	v_mov_b32_e32 v57, v125
	v_mov_b32_e32 v56, v125
	v_mov_b32_e32 v55, v125
	v_mov_b32_e32 v54, v125
	v_mov_b32_e32 v49, v125
	v_mov_b32_e32 v48, v125
	v_mov_b32_e32 v47, v125
	v_mov_b32_e32 v46, v125
	v_mov_b32_e32 v41, v125
	v_mov_b32_e32 v40, v125
	v_mov_b32_e32 v39, v125
	v_mov_b32_e32 v38, v125
	v_mov_b32_e32 v33, v125
	v_mov_b32_e32 v32, v125
	v_mov_b32_e32 v31, v125
	v_mov_b32_e32 v30, v125
	v_mov_b32_e32 v25, v125
	v_mov_b32_e32 v24, v125
	v_mov_b32_e32 v23, v125
	v_mov_b32_e32 v22, v125
	v_mov_b32_e32 v17, v125
	v_mov_b32_e32 v16, v125
	v_mov_b32_e32 v15, v125
	v_mov_b32_e32 v14, v125
	v_mov_b32_e32 v5, v125
	v_mov_b32_e32 v4, v125
	v_mov_b32_e32 v3, v125
	v_mov_b32_e32 v2, v125
	s_cbranch_vccnz .LBB0_1193
	s_add_u32 s68, s68, 0x80
	s_addc_u32 s69, s69, 0
	s_add_u32 s59, s78, 0x100
	v_mov_b32_e32 v2, 0
	s_addc_u32 s60, s79, 0
	s_mov_b32 s61, 0
	v_mov_b32_e32 v3, v2
	v_mov_b32_e32 v4, v2
	v_mov_b32_e32 v5, v2
	v_mov_b32_e32 v14, v2
	v_mov_b32_e32 v15, v2
	v_mov_b32_e32 v16, v2
	v_mov_b32_e32 v17, v2
	v_mov_b32_e32 v22, v2
	v_mov_b32_e32 v23, v2
	v_mov_b32_e32 v24, v2
	v_mov_b32_e32 v25, v2
	v_mov_b32_e32 v30, v2
	v_mov_b32_e32 v31, v2
	v_mov_b32_e32 v32, v2
	v_mov_b32_e32 v33, v2
	v_mov_b32_e32 v38, v2
	v_mov_b32_e32 v39, v2
	v_mov_b32_e32 v40, v2
	v_mov_b32_e32 v41, v2
	v_mov_b32_e32 v46, v2
	v_mov_b32_e32 v47, v2
	v_mov_b32_e32 v48, v2
	v_mov_b32_e32 v49, v2
	v_mov_b32_e32 v54, v2
	v_mov_b32_e32 v55, v2
	v_mov_b32_e32 v56, v2
	v_mov_b32_e32 v57, v2
	v_mov_b32_e32 v62, v2
	v_mov_b32_e32 v63, v2
	v_mov_b32_e32 v64, v2
	v_mov_b32_e32 v65, v2
	v_mov_b32_e32 v6, v2
	v_mov_b32_e32 v7, v2
	v_mov_b32_e32 v8, v2
	v_mov_b32_e32 v9, v2
	v_mov_b32_e32 v10, v2
	v_mov_b32_e32 v11, v2
	v_mov_b32_e32 v12, v2
	v_mov_b32_e32 v13, v2
	v_mov_b32_e32 v18, v2
	v_mov_b32_e32 v19, v2
	v_mov_b32_e32 v20, v2
	v_mov_b32_e32 v21, v2
	v_mov_b32_e32 v26, v2
	v_mov_b32_e32 v27, v2
	v_mov_b32_e32 v28, v2
	v_mov_b32_e32 v29, v2
	v_mov_b32_e32 v34, v2
	v_mov_b32_e32 v35, v2
	v_mov_b32_e32 v36, v2
	v_mov_b32_e32 v37, v2
	v_mov_b32_e32 v42, v2
	v_mov_b32_e32 v43, v2
	v_mov_b32_e32 v44, v2
	v_mov_b32_e32 v45, v2
	v_mov_b32_e32 v50, v2
	v_mov_b32_e32 v51, v2
	v_mov_b32_e32 v52, v2
	v_mov_b32_e32 v53, v2
	v_mov_b32_e32 v58, v2
	v_mov_b32_e32 v59, v2
	v_mov_b32_e32 v60, v2
	v_mov_b32_e32 v61, v2
	v_mov_b32_e32 v70, v2
	v_mov_b32_e32 v71, v2
	v_mov_b32_e32 v72, v2
	v_mov_b32_e32 v73, v2
	v_mov_b32_e32 v78, v2
	v_mov_b32_e32 v79, v2
	v_mov_b32_e32 v80, v2
	v_mov_b32_e32 v81, v2
	v_mov_b32_e32 v86, v2
	v_mov_b32_e32 v87, v2
	v_mov_b32_e32 v88, v2
	v_mov_b32_e32 v89, v2
	v_mov_b32_e32 v94, v2
	v_mov_b32_e32 v95, v2
	v_mov_b32_e32 v96, v2
	v_mov_b32_e32 v97, v2
	v_mov_b32_e32 v102, v2
	v_mov_b32_e32 v103, v2
	v_mov_b32_e32 v104, v2
	v_mov_b32_e32 v105, v2
	v_mov_b32_e32 v110, v2
	v_mov_b32_e32 v111, v2
	v_mov_b32_e32 v112, v2
	v_mov_b32_e32 v113, v2
	v_mov_b32_e32 v118, v2
	v_mov_b32_e32 v119, v2
	v_mov_b32_e32 v120, v2
	v_mov_b32_e32 v121, v2
	v_mov_b32_e32 v126, v2
	v_mov_b32_e32 v127, v2
	v_mov_b32_e32 v128, v2
	v_mov_b32_e32 v129, v2
	v_mov_b32_e32 v66, v2
	v_mov_b32_e32 v67, v2
	v_mov_b32_e32 v68, v2
	v_mov_b32_e32 v69, v2
	v_mov_b32_e32 v74, v2
	v_mov_b32_e32 v75, v2
	v_mov_b32_e32 v76, v2
	v_mov_b32_e32 v77, v2
	v_mov_b32_e32 v82, v2
	v_mov_b32_e32 v83, v2
	v_mov_b32_e32 v84, v2
	v_mov_b32_e32 v85, v2
	v_mov_b32_e32 v90, v2
	v_mov_b32_e32 v91, v2
	v_mov_b32_e32 v92, v2
	v_mov_b32_e32 v93, v2
	v_mov_b32_e32 v98, v2
	v_mov_b32_e32 v99, v2
	v_mov_b32_e32 v100, v2
	v_mov_b32_e32 v101, v2
	v_mov_b32_e32 v106, v2
	v_mov_b32_e32 v107, v2
	v_mov_b32_e32 v108, v2
	v_mov_b32_e32 v109, v2
	v_mov_b32_e32 v114, v2
	v_mov_b32_e32 v115, v2
	v_mov_b32_e32 v116, v2
	v_mov_b32_e32 v117, v2
	v_mov_b32_e32 v122, v2
	v_mov_b32_e32 v123, v2
	v_mov_b32_e32 v124, v2
	v_mov_b32_e32 v125, v2
	.p2alignl 6, 3212836864

; template <class Epi, class Sched, bool ALIGN_EPI = false, bool SP2 = false>
; __device__ __forceinline__ void gemm_phase(PG8_LAS unsigned char* lds, const Gemm g, const Sched& S, const Epi& E) {
;     ...
;     for (;;) {
;         const bool has_next = S.next(ui + 1, nxt);
;         const char* nA = has_next ? (const char*)g.A + (size_t)nxt.pm * tstep : cA; const char* nB = has_next ? (const char*)g.Bt + (size_t)nxt.pn * tstep : cB;
;         for (int t = 0; t < nt; t += 2) {
;     ...
; #pragma unroll
;         for (int a = 0; a < 2; ++a)
; #pragma unroll
;             for (int b = 0; b < 2; ++b)
; #pragma unroll
;                 for (int m = 0; m < 4; ++m)
; #pragma unroll
;                     for (int n = 0; n < 2; ++n) acc[a][b][m][n] = (f32x4){0.f, 0.f, 0.f, 0.f};
;         cur = nxt; cA = nA; cB = nB; ++ui;
.LBB0_1359:
	v_mov_b32_e32 v153, 0
	s_andn2_b64 vcc, exec, s[10:11]
	v_mov_b32_e32 v152, v153
	v_mov_b32_e32 v151, v153
	v_mov_b32_e32 v150, v153
	v_mov_b32_e32 v145, v153
	v_mov_b32_e32 v144, v153
	v_mov_b32_e32 v143, v153
	v_mov_b32_e32 v142, v153
	v_mov_b32_e32 v133, v153
	v_mov_b32_e32 v132, v153
	v_mov_b32_e32 v131, v153
	v_mov_b32_e32 v130, v153
	v_mov_b32_e32 v129, v153
	v_mov_b32_e32 v128, v153
	v_mov_b32_e32 v127, v153
	v_mov_b32_e32 v126, v153
	v_mov_b32_e32 v113, v153
	v_mov_b32_e32 v112, v153
	v_mov_b32_e32 v111, v153
	v_mov_b32_e32 v110, v153
	v_mov_b32_e32 v105, v153
	v_mov_b32_e32 v104, v153
	v_mov_b32_e32 v103, v153
	v_mov_b32_e32 v102, v153
	v_mov_b32_e32 v93, v153
	v_mov_b32_e32 v92, v153
	v_mov_b32_e32 v91, v153
	v_mov_b32_e32 v90, v153
	v_mov_b32_e32 v89, v153
	v_mov_b32_e32 v88, v153
	v_mov_b32_e32 v87, v153
	v_mov_b32_e32 v86, v153
	v_mov_b32_e32 v141, v153
	v_mov_b32_e32 v140, v153
	v_mov_b32_e32 v139, v153
	v_mov_b32_e32 v138, v153
	v_mov_b32_e32 v137, v153
	v_mov_b32_e32 v136, v153
	v_mov_b32_e32 v135, v153
	v_mov_b32_e32 v134, v153
	v_mov_b32_e32 v125, v153
	v_mov_b32_e32 v124, v153
	v_mov_b32_e32 v123, v153
	v_mov_b32_e32 v122, v153
	v_mov_b32_e32 v121, v153
	v_mov_b32_e32 v120, v153
	v_mov_b32_e32 v119, v153
	v_mov_b32_e32 v118, v153
	v_mov_b32_e32 v101, v153
	v_mov_b32_e32 v100, v153
	v_mov_b32_e32 v99, v153
	v_mov_b32_e32 v98, v153
	v_mov_b32_e32 v97, v153
	v_mov_b32_e32 v96, v153
	v_mov_b32_e32 v95, v153
	v_mov_b32_e32 v94, v153
	v_mov_b32_e32 v85, v153
	v_mov_b32_e32 v84, v153
	v_mov_b32_e32 v83, v153
	v_mov_b32_e32 v82, v153
	v_mov_b32_e32 v81, v153
	v_mov_b32_e32 v80, v153
	v_mov_b32_e32 v79, v153
	v_mov_b32_e32 v78, v153
	v_mov_b32_e32 v73, v153
	v_mov_b32_e32 v72, v153
	v_mov_b32_e32 v71, v153
	v_mov_b32_e32 v70, v153
	v_mov_b32_e32 v65, v153
	v_mov_b32_e32 v64, v153
	v_mov_b32_e32 v63, v153
	v_mov_b32_e32 v62, v153
	v_mov_b32_e32 v53, v153
	v_mov_b32_e32 v52, v153
	v_mov_b32_e32 v51, v153
	v_mov_b32_e32 v50, v153
	v_mov_b32_e32 v49, v153
	v_mov_b32_e32 v48, v153
	v_mov_b32_e32 v47, v153
	v_mov_b32_e32 v46, v153
	v_mov_b32_e32 v33, v153
	v_mov_b32_e32 v32, v153
	v_mov_b32_e32 v31, v153
	v_mov_b32_e32 v30, v153
	v_mov_b32_e32 v29, v153
	v_mov_b32_e32 v28, v153
	v_mov_b32_e32 v27, v153
	v_mov_b32_e32 v26, v153
	v_mov_b32_e32 v17, v153
	v_mov_b32_e32 v16, v153
	v_mov_b32_e32 v15, v153
	v_mov_b32_e32 v14, v153
	v_mov_b32_e32 v13, v153
	v_mov_b32_e32 v12, v153
	v_mov_b32_e32 v11, v153
	v_mov_b32_e32 v10, v153
	v_mov_b32_e32 v61, v153
	v_mov_b32_e32 v60, v153
	v_mov_b32_e32 v59, v153
	v_mov_b32_e32 v58, v153
	v_mov_b32_e32 v57, v153
	v_mov_b32_e32 v56, v153
	v_mov_b32_e32 v55, v153
	v_mov_b32_e32 v54, v153
	v_mov_b32_e32 v45, v153
	v_mov_b32_e32 v44, v153
	v_mov_b32_e32 v43, v153
	v_mov_b32_e32 v42, v153
	v_mov_b32_e32 v41, v153
	v_mov_b32_e32 v40, v153
	v_mov_b32_e32 v39, v153
	v_mov_b32_e32 v38, v153
	v_mov_b32_e32 v25, v153
	v_mov_b32_e32 v24, v153
	v_mov_b32_e32 v23, v153
	v_mov_b32_e32 v22, v153
	v_mov_b32_e32 v21, v153
	v_mov_b32_e32 v20, v153
	v_mov_b32_e32 v19, v153
	v_mov_b32_e32 v18, v153
	v_mov_b32_e32 v9, v153
	v_mov_b32_e32 v8, v153
	v_mov_b32_e32 v7, v153
	v_mov_b32_e32 v6, v153
	v_mov_b32_e32 v5, v153
	v_mov_b32_e32 v4, v153
	v_mov_b32_e32 v3, v153
	v_mov_b32_e32 v2, v153
	s_cbranch_vccnz .LBB0_1362
	s_add_u32 s78, s78, 0x80
	s_addc_u32 s79, s79, 0
	s_add_u32 s49, s80, 0x100
	v_mov_b32_e32 v2, 0
	s_addc_u32 s50, s81, 0
	s_mov_b32 s51, 0
	v_mov_b32_e32 v3, v2
	v_mov_b32_e32 v4, v2
	v_mov_b32_e32 v5, v2
	v_mov_b32_e32 v6, v2
	v_mov_b32_e32 v7, v2
	v_mov_b32_e32 v8, v2
	v_mov_b32_e32 v9, v2
	v_mov_b32_e32 v18, v2
	v_mov_b32_e32 v19, v2
	v_mov_b32_e32 v20, v2
	v_mov_b32_e32 v21, v2
	v_mov_b32_e32 v22, v2
	v_mov_b32_e32 v23, v2
	v_mov_b32_e32 v24, v2
	v_mov_b32_e32 v25, v2
	v_mov_b32_e32 v38, v2
	v_mov_b32_e32 v39, v2
	v_mov_b32_e32 v40, v2
	v_mov_b32_e32 v41, v2
	v_mov_b32_e32 v42, v2
	v_mov_b32_e32 v43, v2
	v_mov_b32_e32 v44, v2
	v_mov_b32_e32 v45, v2
	v_mov_b32_e32 v54, v2
	v_mov_b32_e32 v55, v2
	v_mov_b32_e32 v56, v2
	v_mov_b32_e32 v57, v2
	v_mov_b32_e32 v58, v2
	v_mov_b32_e32 v59, v2
	v_mov_b32_e32 v60, v2
	v_mov_b32_e32 v61, v2
	v_mov_b32_e32 v10, v2
	v_mov_b32_e32 v11, v2
	v_mov_b32_e32 v12, v2
	v_mov_b32_e32 v13, v2
	v_mov_b32_e32 v14, v2
	v_mov_b32_e32 v15, v2
	v_mov_b32_e32 v16, v2
	v_mov_b32_e32 v17, v2
	v_mov_b32_e32 v26, v2
	v_mov_b32_e32 v27, v2
	v_mov_b32_e32 v28, v2
	v_mov_b32_e32 v29, v2
	v_mov_b32_e32 v30, v2
	v_mov_b32_e32 v31, v2
	v_mov_b32_e32 v32, v2
	v_mov_b32_e32 v33, v2
	v_mov_b32_e32 v46, v2
	v_mov_b32_e32 v47, v2
	v_mov_b32_e32 v48, v2
	v_mov_b32_e32 v49, v2
	v_mov_b32_e32 v50, v2
	v_mov_b32_e32 v51, v2
	v_mov_b32_e32 v52, v2
	v_mov_b32_e32 v53, v2
	v_mov_b32_e32 v62, v2
	v_mov_b32_e32 v63, v2
	v_mov_b32_e32 v64, v2
	v_mov_b32_e32 v65, v2
	v_mov_b32_e32 v70, v2
	v_mov_b32_e32 v71, v2
	v_mov_b32_e32 v72, v2
	v_mov_b32_e32 v73, v2
	v_mov_b32_e32 v78, v2
	v_mov_b32_e32 v79, v2
	v_mov_b32_e32 v80, v2
	v_mov_b32_e32 v81, v2
	v_mov_b32_e32 v82, v2
	v_mov_b32_e32 v83, v2
	v_mov_b32_e32 v84, v2
	v_mov_b32_e32 v85, v2
	v_mov_b32_e32 v94, v2
	v_mov_b32_e32 v95, v2
	v_mov_b32_e32 v96, v2
	v_mov_b32_e32 v97, v2
	v_mov_b32_e32 v98, v2
	v_mov_b32_e32 v99, v2
	v_mov_b32_e32 v100, v2
	v_mov_b32_e32 v101, v2
	v_mov_b32_e32 v118, v2
	v_mov_b32_e32 v119, v2
	v_mov_b32_e32 v120, v2
	v_mov_b32_e32 v121, v2
	v_mov_b32_e32 v122, v2
	v_mov_b32_e32 v123, v2
	v_mov_b32_e32 v124, v2
	v_mov_b32_e32 v125, v2
	v_mov_b32_e32 v134, v2
	v_mov_b32_e32 v135, v2
	v_mov_b32_e32 v136, v2
	v_mov_b32_e32 v137, v2
	v_mov_b32_e32 v138, v2
	v_mov_b32_e32 v139, v2
	v_mov_b32_e32 v140, v2
	v_mov_b32_e32 v141, v2
	v_mov_b32_e32 v86, v2
	v_mov_b32_e32 v87, v2
	v_mov_b32_e32 v88, v2
	v_mov_b32_e32 v89, v2
	v_mov_b32_e32 v90, v2
	v_mov_b32_e32 v91, v2
	v_mov_b32_e32 v92, v2
	v_mov_b32_e32 v93, v2
	v_mov_b32_e32 v102, v2
	v_mov_b32_e32 v103, v2
	v_mov_b32_e32 v104, v2
	v_mov_b32_e32 v105, v2
	v_mov_b32_e32 v110, v2
	v_mov_b32_e32 v111, v2
	v_mov_b32_e32 v112, v2
	v_mov_b32_e32 v113, v2
	v_mov_b32_e32 v126, v2
	v_mov_b32_e32 v127, v2
	v_mov_b32_e32 v128, v2
	v_mov_b32_e32 v129, v2
	v_mov_b32_e32 v130, v2
	v_mov_b32_e32 v131, v2
	v_mov_b32_e32 v132, v2
	v_mov_b32_e32 v133, v2
	v_mov_b32_e32 v142, v2
	v_mov_b32_e32 v143, v2
	v_mov_b32_e32 v144, v2
	v_mov_b32_e32 v145, v2
	v_mov_b32_e32 v150, v2
	v_mov_b32_e32 v151, v2
	v_mov_b32_e32 v152, v2
	v_mov_b32_e32 v153, v2
	.p2alignl 6, 3212836864
